# P1 rotary epilogue: o1/o2 of a wave stored to adjacent 64B halves of one line (fixed dk permutation inside each retention head for q_r and k_r) + lane-pair swap -> full-line stores
# baseline (speedup 1.0000x reference)
; __device__ __forceinline__ unsigned cvt_pk_bf16(float lo, float hi) { unsigned r; asm volatile("v_cvt_pk_bf16_f32 %0, %1, %2" : "=v"(r) : "v"(lo), "v"(hi)); return r; }
;     __device__ __forceinline__ void operator()(const f32x4 (&acc)[2][2][4][2], const pg8::Unit& u, int wr, int wc, int fr, int fq) const {
;     ...
;         } else if (sec == 4 || sec == 5) {
;             const float osc = sec == 5 ? 0.08838834764831845f : 1.f;
;             const int col0 = 256 * half + 128 * (wc >> 1) + 32 * (wc & 1) + 8 * fq, i0 = 32 * (wc & 1) + 8 * fq;
;             const int tb = row0 < NP ? (row0 & 4095) : row0 - NP;
;             f32x4 c[2], sn[2], c16[2], s16[2];
; #pragma unroll
;             for (int e = 0; e < 2; ++e) { c[e] = *(const f32x4*)(ropec + tb * 64 + i0 + 4 * e); sn[e] = *(const f32x4*)(ropes + tb * 64 + i0 + 4 * e);
;                 c16[e] = *(const f32x4*)(ropec + 16 * 64 + i0 + 4 * e); s16[e] = *(const f32x4*)(ropes + 16 * 64 + i0 + 4 * e); }
;             asm volatile("" ::: "memory");
; #pragma unroll
;             for (int k = 0; k < 12; ++k) {
;                 if (k < 4 || k >= 8) {
;                     const int ai = k >> 3, m = k & 3;
;                     const int row = row0 + ai * 128 + m * 16;
;                     const f32x4 c0 = c[0] * osc, c1 = c[1] * osc, s0 = sn[0] * osc, s1 = sn[1] * osc;
;                     const f32x4 a0 = acc[ai][0][m][0], a1 = acc[ai][0][m][1], b0 = acc[ai][1][m][0], b1 = acc[ai][1][m][1];
;                     const f32x4 o10 = a0 * c0 - b0 * s0, o11 = a1 * c1 - b1 * s1, o20 = a0 * s0 + b0 * c0, o21 = a1 * s1 + b1 * c1;
;                     bf16_t* rowp = base + (size_t)row * 512 + col0;
;                     u32x4 w; w.x = cvt_pk_bf16(o10[0], o10[1]); w.y = cvt_pk_bf16(o10[2], o10[3]); w.z = cvt_pk_bf16(o11[0], o11[1]); w.w = cvt_pk_bf16(o11[2], o11[3]);
;                     *(u32x4*)(rowp) = w;
;                     w.x = cvt_pk_bf16(o20[0], o20[1]); w.y = cvt_pk_bf16(o20[2], o20[3]); w.z = cvt_pk_bf16(o21[0], o21[1]); w.w = cvt_pk_bf16(o21[2], o21[3]);
;                     *(u32x4*)(rowp + 64) = w;
.LBB0_202:
	s_and_b64 vcc, exec, s[4:5]
	s_cbranch_vccz .LBB0_204
	v_and_b32_e32 v252, 1, v172
	v_sub_u32_e32 v253, 0, v252
	v_and_b32_e32 v252, 0xfffffc40, v253
	s_and_b32 s94, s97, 1
	s_lshl_b32 s94, s94, 6
	s_mov_b32 s95, 0
	v_lshl_add_u64 v[252:253], v[252:253], 0, s[94:95]
	s_mov_b32 s94, 0x55555555
	s_mov_b32 s95, 0x55555555
	v_and_b32_e32 v130, 0xfcf, v172
	v_add_u32_e32 v131, 0xffff0000, v172
	v_cmp_gt_i32_e32 vcc, s77, v172
	s_cmp_eq_u32 s41, 5
	v_lshl_or_b32 v154, s27, 9, v186
	v_cndmask_b32_e32 v130, v131, v130, vcc
	v_lshlrev_b32_e32 v130, 6, v130
	v_ashrrev_i32_e32 v131, 31, v130
	v_lshlrev_b64 v[130:131], 2, v[130:131]
	v_lshl_add_u64 v[132:133], v[156:157], 0, v[130:131]
	global_load_dwordx4 v[192:195], v[132:133], off
	global_load_dwordx4 v[196:199], v[132:133], off offset:16
	v_lshl_add_u64 v[130:131], v[158:159], 0, v[130:131]
	global_load_dwordx4 v[200:203], v[130:131], off
	global_load_dwordx4 v[204:207], v[130:131], off offset:16
	global_load_dwordx4 v[142:145], v[162:163], off
	global_load_dwordx4 v[134:137], v[162:163], off offset:16
	global_load_dwordx4 v[138:141], v[160:161], off
	s_nop 0
	global_load_dwordx4 v[130:133], v[160:161], off offset:16
	s_cselect_b64 vcc, -1, 0
	v_cndmask_b32_e32 v176, 1.0, v189, vcc
	v_ashrrev_i32_e32 v173, 31, v172
	v_lshl_add_u64 v[178:179], s[48:49], 0, v[154:155]
	v_lshlrev_b64 v[174:175], 10, v[172:173]
	v_lshl_add_u64 v[174:175], v[178:179], 0, v[174:175]
	v_or_b32_e32 v208, 16, v172
	v_ashrrev_i32_e32 v209, 31, v208
	s_waitcnt vmcnt(0)
	v_pk_mul_f32 v[220:221], v[176:177], v[200:201] op_sel_hi:[0,1]
	v_pk_mul_f32 v[218:219], v[176:177], v[202:203] op_sel_hi:[0,1]
	v_pk_mul_f32 v[212:213], v[176:177], v[192:193] op_sel_hi:[0,1]
	v_pk_mul_f32 v[228:229], v[200:201], v[142:143]
	v_pk_mul_f32 v[244:245], v[118:119], v[220:221]
	v_pk_mul_f32 v[210:211], v[176:177], v[194:195] op_sel_hi:[0,1]
	v_pk_mul_f32 v[222:223], v[176:177], v[206:207] op_sel_hi:[0,1]
	v_pk_mul_f32 v[224:225], v[176:177], v[204:205] op_sel_hi:[0,1]
	v_pk_mul_f32 v[226:227], v[202:203], v[144:145]
	v_pk_mul_f32 v[230:231], v[194:195], v[144:145]
	v_pk_mul_f32 v[232:233], v[192:193], v[142:143]
	v_pk_mul_f32 v[242:243], v[120:121], v[218:219]
	v_pk_fma_f32 v[228:229], v[192:193], v[138:139], v[228:229] neg_lo:[0,0,1] neg_hi:[0,0,1]
	v_pk_fma_f32 v[192:193], v[126:127], v[212:213], v[244:245] neg_lo:[0,0,1] neg_hi:[0,0,1]
	v_pk_mul_f32 v[214:215], v[176:177], v[198:199] op_sel_hi:[0,1]
	v_pk_mul_f32 v[216:217], v[176:177], v[196:197] op_sel_hi:[0,1]
	v_pk_mul_f32 v[234:235], v[206:207], v[136:137]
	v_pk_mul_f32 v[238:239], v[198:199], v[136:137]
	v_pk_mul_f32 v[240:241], v[196:197], v[134:135]
	v_pk_mul_f32 v[246:247], v[116:117], v[222:223]
	v_pk_mul_f32 v[248:249], v[114:115], v[224:225]
	v_pk_mul_f32 v[218:219], v[128:129], v[218:219]
	v_pk_mul_f32 v[220:221], v[126:127], v[220:221]
	v_pk_fma_f32 v[226:227], v[194:195], v[140:141], v[226:227] neg_lo:[0,0,1] neg_hi:[0,0,1]
	v_pk_fma_f32 v[202:203], v[202:203], v[140:141], v[230:231]
	v_pk_fma_f32 v[194:195], v[128:129], v[210:211], v[242:243] neg_lo:[0,0,1] neg_hi:[0,0,1]
	v_cvt_pk_bf16_f32 v192, v192, v193
	v_pk_mul_f32 v[236:237], v[204:205], v[134:135]
	v_cvt_pk_bf16_f32 v193, v194, v195
	v_pk_mul_f32 v[222:223], v[124:125], v[222:223]
	v_pk_mul_f32 v[224:225], v[122:123], v[224:225]
	v_pk_fma_f32 v[200:201], v[200:201], v[138:139], v[232:233]
	v_pk_fma_f32 v[198:199], v[198:199], v[132:133], v[234:235] neg_lo:[0,0,1] neg_hi:[0,0,1]
	v_pk_fma_f32 v[206:207], v[206:207], v[132:133], v[238:239]
	v_pk_fma_f32 v[204:205], v[204:205], v[130:131], v[240:241]
	v_pk_fma_f32 v[230:231], v[124:125], v[214:215], v[246:247] neg_lo:[0,0,1] neg_hi:[0,0,1]
	v_pk_fma_f32 v[232:233], v[122:123], v[216:217], v[248:249] neg_lo:[0,0,1] neg_hi:[0,0,1]
	v_pk_fma_f32 v[210:211], v[120:121], v[210:211], v[218:219]
	v_pk_fma_f32 v[212:213], v[118:119], v[212:213], v[220:221]
	v_pk_mul_f32 v[218:219], v[176:177], v[226:227] op_sel_hi:[0,1]
	v_pk_mul_f32 v[234:235], v[176:177], v[202:203] op_sel_hi:[0,1]
	v_cvt_pk_bf16_f32 v194, v232, v233
	v_cvt_pk_bf16_f32 v195, v230, v231
	v_mov_b32_e32 v118, v192
	v_mov_b32_e32 v119, v193
	v_mov_b32_e32 v120, v194
	v_mov_b32_e32 v121, v195
	v_lshl_add_u64 v[124:125], v[174:175], 0, v[252:253]
	v_pk_fma_f32 v[196:197], v[196:197], v[130:131], v[236:237] neg_lo:[0,0,1] neg_hi:[0,0,1]
	v_pk_fma_f32 v[214:215], v[116:117], v[214:215], v[222:223]
	v_cvt_pk_bf16_f32 v192, v212, v213
	v_cvt_pk_bf16_f32 v193, v210, v211
	v_pk_fma_f32 v[216:217], v[114:115], v[216:217], v[224:225]
	v_pk_mul_f32 v[222:223], v[176:177], v[198:199] op_sel_hi:[0,1]
	v_pk_mul_f32 v[238:239], v[176:177], v[206:207] op_sel_hi:[0,1]
	v_pk_mul_f32 v[240:241], v[176:177], v[204:205] op_sel_hi:[0,1]
	v_pk_mul_f32 v[230:231], v[104:105], v[234:235]
	v_cvt_pk_bf16_f32 v194, v216, v217
	v_cvt_pk_bf16_f32 v195, v214, v215
	s_nop 1
	v_mov_b32_dpp v122, v118 quad_perm:[1,0,3,2] row_mask:0xf bank_mask:0xf
	v_mov_b32_dpp v123, v192 quad_perm:[1,0,3,2] row_mask:0xf bank_mask:0xf
	v_cndmask_b32_e64 v118, v123, v118, s[94:95]
	v_cndmask_b32_e64 v192, v192, v122, s[94:95]
	v_mov_b32_dpp v122, v119 quad_perm:[1,0,3,2] row_mask:0xf bank_mask:0xf
	v_mov_b32_dpp v123, v193 quad_perm:[1,0,3,2] row_mask:0xf bank_mask:0xf
	v_cndmask_b32_e64 v119, v123, v119, s[94:95]
	v_cndmask_b32_e64 v193, v193, v122, s[94:95]
	v_mov_b32_dpp v122, v120 quad_perm:[1,0,3,2] row_mask:0xf bank_mask:0xf
	v_mov_b32_dpp v123, v194 quad_perm:[1,0,3,2] row_mask:0xf bank_mask:0xf
	v_cndmask_b32_e64 v120, v123, v120, s[94:95]
	v_cndmask_b32_e64 v194, v194, v122, s[94:95]
	v_mov_b32_dpp v122, v121 quad_perm:[1,0,3,2] row_mask:0xf bank_mask:0xf
; __device__ __forceinline__ unsigned cvt_pk_bf16(float lo, float hi) { unsigned r; asm volatile("v_cvt_pk_bf16_f32 %0, %1, %2" : "=v"(r) : "v"(lo), "v"(hi)); return r; }
;     __device__ __forceinline__ void operator()(const f32x4 (&acc)[2][2][4][2], const pg8::Unit& u, int wr, int wc, int fr, int fq) const {
;     ...
;             for (int k = 0; k < 12; ++k) {
;                 if (k < 4 || k >= 8) {
;                     const int ai = k >> 3, m = k & 3;
;                     const int row = row0 + ai * 128 + m * 16;
;                     const f32x4 c0 = c[0] * osc, c1 = c[1] * osc, s0 = sn[0] * osc, s1 = sn[1] * osc;
;                     const f32x4 a0 = acc[ai][0][m][0], a1 = acc[ai][0][m][1], b0 = acc[ai][1][m][0], b1 = acc[ai][1][m][1];
;                     const f32x4 o10 = a0 * c0 - b0 * s0, o11 = a1 * c1 - b1 * s1, o20 = a0 * s0 + b0 * c0, o21 = a1 * s1 + b1 * c1;
;                     bf16_t* rowp = base + (size_t)row * 512 + col0;
;                     u32x4 w; w.x = cvt_pk_bf16(o10[0], o10[1]); w.y = cvt_pk_bf16(o10[2], o10[3]); w.z = cvt_pk_bf16(o11[0], o11[1]); w.w = cvt_pk_bf16(o11[2], o11[3]);
;                     *(u32x4*)(rowp) = w;
;                     w.x = cvt_pk_bf16(o20[0], o20[1]); w.y = cvt_pk_bf16(o20[2], o20[3]); w.z = cvt_pk_bf16(o21[0], o21[1]); w.w = cvt_pk_bf16(o21[2], o21[3]);
;                     *(u32x4*)(rowp + 64) = w;
;                 }
;                 if (k < 11) {
; #pragma unroll
;                     for (int e = 0; e < 2; ++e) { const f32x4 cn = c[e] * c16[e] - sn[e] * s16[e]; sn[e] = sn[e] * c16[e] + c[e] * s16[e]; c[e] = cn; } }
	v_mov_b32_dpp v123, v195 quad_perm:[1,0,3,2] row_mask:0xf bank_mask:0xf
	v_cndmask_b32_e64 v121, v123, v121, s[94:95]
	v_cndmask_b32_e64 v195, v195, v122, s[94:95]
	global_store_dwordx4 v[124:125], v[118:121], off
	global_store_dwordx4 v[124:125], v[192:195], off offset:1024
	v_pk_mul_f32 v[224:225], v[176:177], v[196:197] op_sel_hi:[0,1]
	v_pk_mul_f32 v[236:237], v[176:177], v[200:201] op_sel_hi:[0,1]
	v_pk_mul_f32 v[192:193], v[104:105], v[218:219]
	v_pk_mul_f32 v[242:243], v[100:101], v[238:239]
	v_pk_mul_f32 v[244:245], v[98:99], v[240:241]
	v_pk_fma_f32 v[210:211], v[112:113], v[218:219], v[230:231] neg_lo:[0,0,1] neg_hi:[0,0,1]
	v_pk_fma_f32 v[218:219], v[112:113], v[234:235], v[192:193]
	v_pk_mul_f32 v[192:193], v[100:101], v[222:223]
	v_pk_mul_f32 v[220:221], v[176:177], v[228:229] op_sel_hi:[0,1]
	v_pk_mul_f32 v[232:233], v[102:103], v[236:237]
	v_pk_fma_f32 v[214:215], v[108:109], v[222:223], v[242:243] neg_lo:[0,0,1] neg_hi:[0,0,1]
	v_pk_fma_f32 v[194:195], v[106:107], v[224:225], v[244:245] neg_lo:[0,0,1] neg_hi:[0,0,1]
	v_pk_fma_f32 v[222:223], v[108:109], v[238:239], v[192:193]
	v_lshlrev_b64 v[192:193], 10, v[208:209]
	v_pk_fma_f32 v[212:213], v[110:111], v[220:221], v[232:233] neg_lo:[0,0,1] neg_hi:[0,0,1]
	v_pk_mul_f32 v[216:217], v[102:103], v[220:221]
	v_pk_mul_f32 v[220:221], v[98:99], v[224:225]
	v_lshl_add_u64 v[208:209], v[178:179], 0, v[192:193]
	v_cvt_pk_bf16_f32 v192, v212, v213
	v_cvt_pk_bf16_f32 v193, v210, v211
	v_cvt_pk_bf16_f32 v194, v194, v195
	v_cvt_pk_bf16_f32 v195, v214, v215
	v_pk_fma_f32 v[216:217], v[110:111], v[236:237], v[216:217]
	v_pk_fma_f32 v[220:221], v[106:107], v[240:241], v[220:221]
	v_mov_b32_e32 v118, v192
	v_mov_b32_e32 v119, v193
	v_mov_b32_e32 v120, v194
	v_mov_b32_e32 v121, v195
	v_lshl_add_u64 v[124:125], v[208:209], 0, v[252:253]
	s_nop 1
	v_cvt_pk_bf16_f32 v192, v216, v217
	v_cvt_pk_bf16_f32 v193, v218, v219
	v_cvt_pk_bf16_f32 v194, v220, v221
	v_cvt_pk_bf16_f32 v195, v222, v223
	s_nop 1
	v_mov_b32_dpp v122, v118 quad_perm:[1,0,3,2] row_mask:0xf bank_mask:0xf
	v_mov_b32_dpp v123, v192 quad_perm:[1,0,3,2] row_mask:0xf bank_mask:0xf
	v_cndmask_b32_e64 v118, v123, v118, s[94:95]
	v_cndmask_b32_e64 v192, v192, v122, s[94:95]
	v_mov_b32_dpp v122, v119 quad_perm:[1,0,3,2] row_mask:0xf bank_mask:0xf
	v_mov_b32_dpp v123, v193 quad_perm:[1,0,3,2] row_mask:0xf bank_mask:0xf
	v_cndmask_b32_e64 v119, v123, v119, s[94:95]
	v_cndmask_b32_e64 v193, v193, v122, s[94:95]
	v_mov_b32_dpp v122, v120 quad_perm:[1,0,3,2] row_mask:0xf bank_mask:0xf
	v_mov_b32_dpp v123, v194 quad_perm:[1,0,3,2] row_mask:0xf bank_mask:0xf
	v_cndmask_b32_e64 v120, v123, v120, s[94:95]
	v_cndmask_b32_e64 v194, v194, v122, s[94:95]
	v_mov_b32_dpp v122, v121 quad_perm:[1,0,3,2] row_mask:0xf bank_mask:0xf
	v_mov_b32_dpp v123, v195 quad_perm:[1,0,3,2] row_mask:0xf bank_mask:0xf
	v_cndmask_b32_e64 v121, v123, v121, s[94:95]
	v_cndmask_b32_e64 v195, v195, v122, s[94:95]
	global_store_dwordx4 v[124:125], v[118:121], off
	global_store_dwordx4 v[124:125], v[192:195], off offset:1024
	s_nop 1
	v_pk_mul_f32 v[192:193], v[144:145], v[202:203]
	v_pk_mul_f32 v[194:195], v[142:143], v[200:201]
	v_pk_fma_f32 v[208:209], v[140:141], v[226:227], v[192:193] neg_lo:[0,0,1] neg_hi:[0,0,1]
	v_pk_fma_f32 v[210:211], v[138:139], v[228:229], v[194:195] neg_lo:[0,0,1] neg_hi:[0,0,1]
	v_pk_mul_f32 v[192:193], v[144:145], v[226:227]
	v_pk_mul_f32 v[194:195], v[142:143], v[228:229]
	v_pk_fma_f32 v[202:203], v[140:141], v[202:203], v[192:193]
	v_pk_fma_f32 v[200:201], v[138:139], v[200:201], v[194:195]
	v_pk_mul_f32 v[192:193], v[136:137], v[206:207]
	v_pk_mul_f32 v[194:195], v[134:135], v[204:205]
	v_pk_fma_f32 v[212:213], v[132:133], v[198:199], v[192:193] neg_lo:[0,0,1] neg_hi:[0,0,1]
	v_pk_fma_f32 v[214:215], v[130:131], v[196:197], v[194:195] neg_lo:[0,0,1] neg_hi:[0,0,1]
	v_pk_mul_f32 v[192:193], v[136:137], v[198:199]
	v_pk_mul_f32 v[194:195], v[134:135], v[196:197]
	v_pk_mul_f32 v[218:219], v[176:177], v[202:203] op_sel_hi:[0,1]
	v_pk_fma_f32 v[196:197], v[132:133], v[206:207], v[192:193]
	v_pk_fma_f32 v[198:199], v[130:131], v[204:205], v[194:195]
	v_or_b32_e32 v192, 32, v172
	v_pk_mul_f32 v[194:195], v[176:177], v[208:209] op_sel_hi:[0,1]
	v_pk_mul_f32 v[220:221], v[176:177], v[200:201] op_sel_hi:[0,1]
	v_pk_mul_f32 v[226:227], v[88:89], v[218:219]
	v_pk_mul_f32 v[204:205], v[176:177], v[210:211] op_sel_hi:[0,1]
	v_pk_mul_f32 v[206:207], v[176:177], v[212:213] op_sel_hi:[0,1]
	v_pk_mul_f32 v[222:223], v[176:177], v[196:197] op_sel_hi:[0,1]
	v_pk_mul_f32 v[224:225], v[176:177], v[198:199] op_sel_hi:[0,1]
	v_pk_mul_f32 v[228:229], v[86:87], v[220:221]
	v_pk_fma_f32 v[226:227], v[96:97], v[194:195], v[226:227] neg_lo:[0,0,1] neg_hi:[0,0,1]
	v_pk_mul_f32 v[194:195], v[88:89], v[194:195]
	v_ashrrev_i32_e32 v193, 31, v192
	v_pk_mul_f32 v[216:217], v[176:177], v[214:215] op_sel_hi:[0,1]
	v_pk_fma_f32 v[228:229], v[94:95], v[204:205], v[228:229] neg_lo:[0,0,1] neg_hi:[0,0,1]
	v_pk_mul_f32 v[230:231], v[84:85], v[222:223]
	v_pk_mul_f32 v[232:233], v[82:83], v[224:225]
	v_pk_mul_f32 v[204:205], v[86:87], v[204:205]
	v_pk_fma_f32 v[218:219], v[96:97], v[218:219], v[194:195]
	v_pk_mul_f32 v[194:195], v[84:85], v[206:207]
	v_lshlrev_b64 v[192:193], 10, v[192:193]
	v_pk_fma_f32 v[230:231], v[92:93], v[206:207], v[230:231] neg_lo:[0,0,1] neg_hi:[0,0,1]
	v_pk_fma_f32 v[232:233], v[90:91], v[216:217], v[232:233] neg_lo:[0,0,1] neg_hi:[0,0,1]
	v_pk_fma_f32 v[204:205], v[94:95], v[220:221], v[204:205]
	v_pk_mul_f32 v[206:207], v[82:83], v[216:217]
	v_pk_fma_f32 v[216:217], v[92:93], v[222:223], v[194:195]
	v_lshl_add_u64 v[220:221], v[178:179], 0, v[192:193]
; __device__ __forceinline__ unsigned cvt_pk_bf16(float lo, float hi) { unsigned r; asm volatile("v_cvt_pk_bf16_f32 %0, %1, %2" : "=v"(r) : "v"(lo), "v"(hi)); return r; }
;     __device__ __forceinline__ void operator()(const f32x4 (&acc)[2][2][4][2], const pg8::Unit& u, int wr, int wc, int fr, int fq) const {
;     ...
;             for (int k = 0; k < 12; ++k) {
;                 if (k < 4 || k >= 8) {
;                     const int ai = k >> 3, m = k & 3;
;                     const int row = row0 + ai * 128 + m * 16;
;                     const f32x4 c0 = c[0] * osc, c1 = c[1] * osc, s0 = sn[0] * osc, s1 = sn[1] * osc;
;                     const f32x4 a0 = acc[ai][0][m][0], a1 = acc[ai][0][m][1], b0 = acc[ai][1][m][0], b1 = acc[ai][1][m][1];
;                     const f32x4 o10 = a0 * c0 - b0 * s0, o11 = a1 * c1 - b1 * s1, o20 = a0 * s0 + b0 * c0, o21 = a1 * s1 + b1 * c1;
;                     bf16_t* rowp = base + (size_t)row * 512 + col0;
;                     u32x4 w; w.x = cvt_pk_bf16(o10[0], o10[1]); w.y = cvt_pk_bf16(o10[2], o10[3]); w.z = cvt_pk_bf16(o11[0], o11[1]); w.w = cvt_pk_bf16(o11[2], o11[3]);
;                     *(u32x4*)(rowp) = w;
;                     w.x = cvt_pk_bf16(o20[0], o20[1]); w.y = cvt_pk_bf16(o20[2], o20[3]); w.z = cvt_pk_bf16(o21[0], o21[1]); w.w = cvt_pk_bf16(o21[2], o21[3]);
;                     *(u32x4*)(rowp + 64) = w;
;                 }
;                 if (k < 11) {
; #pragma unroll
;                     for (int e = 0; e < 2; ++e) { const f32x4 cn = c[e] * c16[e] - sn[e] * s16[e]; sn[e] = sn[e] * c16[e] + c[e] * s16[e]; c[e] = cn; } }
;             }
	v_cvt_pk_bf16_f32 v192, v228, v229
	v_cvt_pk_bf16_f32 v193, v226, v227
	v_cvt_pk_bf16_f32 v194, v232, v233
	v_cvt_pk_bf16_f32 v195, v230, v231
	v_pk_fma_f32 v[206:207], v[90:91], v[224:225], v[206:207]
	v_mov_b32_e32 v118, v192
	v_mov_b32_e32 v119, v193
	v_mov_b32_e32 v120, v194
	v_mov_b32_e32 v121, v195
	v_lshl_add_u64 v[124:125], v[220:221], 0, v[252:253]
	s_nop 1
	v_cvt_pk_bf16_f32 v192, v204, v205
	v_cvt_pk_bf16_f32 v193, v218, v219
	v_cvt_pk_bf16_f32 v194, v206, v207
	v_cvt_pk_bf16_f32 v195, v216, v217
	s_nop 1
	v_mov_b32_dpp v122, v118 quad_perm:[1,0,3,2] row_mask:0xf bank_mask:0xf
	v_mov_b32_dpp v123, v192 quad_perm:[1,0,3,2] row_mask:0xf bank_mask:0xf
	v_cndmask_b32_e64 v118, v123, v118, s[94:95]
	v_cndmask_b32_e64 v192, v192, v122, s[94:95]
	v_mov_b32_dpp v122, v119 quad_perm:[1,0,3,2] row_mask:0xf bank_mask:0xf
	v_mov_b32_dpp v123, v193 quad_perm:[1,0,3,2] row_mask:0xf bank_mask:0xf
	v_cndmask_b32_e64 v119, v123, v119, s[94:95]
	v_cndmask_b32_e64 v193, v193, v122, s[94:95]
	v_mov_b32_dpp v122, v120 quad_perm:[1,0,3,2] row_mask:0xf bank_mask:0xf
	v_mov_b32_dpp v123, v194 quad_perm:[1,0,3,2] row_mask:0xf bank_mask:0xf
	v_cndmask_b32_e64 v120, v123, v120, s[94:95]
	v_cndmask_b32_e64 v194, v194, v122, s[94:95]
	v_mov_b32_dpp v122, v121 quad_perm:[1,0,3,2] row_mask:0xf bank_mask:0xf
	v_mov_b32_dpp v123, v195 quad_perm:[1,0,3,2] row_mask:0xf bank_mask:0xf
	v_cndmask_b32_e64 v121, v123, v121, s[94:95]
	v_cndmask_b32_e64 v195, v195, v122, s[94:95]
	global_store_dwordx4 v[124:125], v[118:121], off
	global_store_dwordx4 v[124:125], v[192:195], off offset:1024
	s_nop 1
	v_pk_mul_f32 v[192:193], v[144:145], v[202:203]
	v_pk_mul_f32 v[194:195], v[142:143], v[200:201]
	v_pk_fma_f32 v[204:205], v[140:141], v[208:209], v[192:193] neg_lo:[0,0,1] neg_hi:[0,0,1]
	v_pk_fma_f32 v[206:207], v[138:139], v[210:211], v[194:195] neg_lo:[0,0,1] neg_hi:[0,0,1]
	v_pk_mul_f32 v[192:193], v[144:145], v[208:209]
	v_pk_mul_f32 v[194:195], v[142:143], v[210:211]
	v_pk_fma_f32 v[202:203], v[140:141], v[202:203], v[192:193]
	v_pk_fma_f32 v[200:201], v[138:139], v[200:201], v[194:195]
	v_pk_mul_f32 v[192:193], v[136:137], v[196:197]
	v_pk_mul_f32 v[194:195], v[134:135], v[198:199]
	v_pk_fma_f32 v[208:209], v[132:133], v[212:213], v[192:193] neg_lo:[0,0,1] neg_hi:[0,0,1]
	v_pk_fma_f32 v[210:211], v[130:131], v[214:215], v[194:195] neg_lo:[0,0,1] neg_hi:[0,0,1]
	v_pk_mul_f32 v[192:193], v[136:137], v[212:213]
	v_pk_mul_f32 v[194:195], v[134:135], v[214:215]
	v_pk_mul_f32 v[218:219], v[176:177], v[202:203] op_sel_hi:[0,1]
	v_pk_fma_f32 v[196:197], v[132:133], v[196:197], v[192:193]
	v_pk_fma_f32 v[198:199], v[130:131], v[198:199], v[194:195]
	v_or_b32_e32 v192, 48, v172
	v_pk_mul_f32 v[194:195], v[176:177], v[204:205] op_sel_hi:[0,1]
	v_pk_mul_f32 v[226:227], v[72:73], v[218:219]
	v_pk_mul_f32 v[214:215], v[176:177], v[208:209] op_sel_hi:[0,1]
	v_pk_mul_f32 v[220:221], v[176:177], v[200:201] op_sel_hi:[0,1]
	v_pk_mul_f32 v[222:223], v[176:177], v[196:197] op_sel_hi:[0,1]
	v_pk_mul_f32 v[224:225], v[176:177], v[198:199] op_sel_hi:[0,1]
	v_pk_fma_f32 v[226:227], v[80:81], v[194:195], v[226:227] neg_lo:[0,0,1] neg_hi:[0,0,1]
	v_pk_mul_f32 v[194:195], v[72:73], v[194:195]
	v_ashrrev_i32_e32 v193, 31, v192
	v_pk_mul_f32 v[212:213], v[176:177], v[206:207] op_sel_hi:[0,1]
	v_pk_mul_f32 v[216:217], v[176:177], v[210:211] op_sel_hi:[0,1]
	v_pk_mul_f32 v[228:229], v[70:71], v[220:221]
	v_pk_mul_f32 v[230:231], v[68:69], v[222:223]
	v_pk_mul_f32 v[232:233], v[66:67], v[224:225]
	v_pk_fma_f32 v[218:219], v[80:81], v[218:219], v[194:195]
	v_pk_mul_f32 v[194:195], v[68:69], v[214:215]
	v_lshlrev_b64 v[192:193], 10, v[192:193]
	v_pk_fma_f32 v[228:229], v[78:79], v[212:213], v[228:229] neg_lo:[0,0,1] neg_hi:[0,0,1]
	v_pk_fma_f32 v[230:231], v[76:77], v[214:215], v[230:231] neg_lo:[0,0,1] neg_hi:[0,0,1]
	v_pk_fma_f32 v[232:233], v[74:75], v[216:217], v[232:233] neg_lo:[0,0,1] neg_hi:[0,0,1]
	v_pk_mul_f32 v[212:213], v[70:71], v[212:213]
	v_pk_mul_f32 v[214:215], v[66:67], v[216:217]
	v_pk_fma_f32 v[216:217], v[76:77], v[222:223], v[194:195]
	v_lshl_add_u64 v[178:179], v[178:179], 0, v[192:193]
	v_cvt_pk_bf16_f32 v192, v228, v229
	v_cvt_pk_bf16_f32 v193, v226, v227
	v_cvt_pk_bf16_f32 v194, v232, v233
	v_cvt_pk_bf16_f32 v195, v230, v231
	v_pk_fma_f32 v[212:213], v[78:79], v[220:221], v[212:213]
	v_pk_fma_f32 v[214:215], v[74:75], v[224:225], v[214:215]
	v_mov_b32_e32 v118, v192
	v_mov_b32_e32 v119, v193
	v_mov_b32_e32 v120, v194
	v_mov_b32_e32 v121, v195
	v_lshl_add_u64 v[124:125], v[178:179], 0, v[252:253]
	s_nop 1
	v_cvt_pk_bf16_f32 v192, v212, v213
	v_cvt_pk_bf16_f32 v193, v218, v219
	v_cvt_pk_bf16_f32 v194, v214, v215
	v_cvt_pk_bf16_f32 v195, v216, v217
	s_nop 1
	v_mov_b32_dpp v122, v118 quad_perm:[1,0,3,2] row_mask:0xf bank_mask:0xf
	v_mov_b32_dpp v123, v192 quad_perm:[1,0,3,2] row_mask:0xf bank_mask:0xf
	v_cndmask_b32_e64 v118, v123, v118, s[94:95]
	v_cndmask_b32_e64 v192, v192, v122, s[94:95]
	v_mov_b32_dpp v122, v119 quad_perm:[1,0,3,2] row_mask:0xf bank_mask:0xf
	v_mov_b32_dpp v123, v193 quad_perm:[1,0,3,2] row_mask:0xf bank_mask:0xf
	v_cndmask_b32_e64 v119, v123, v119, s[94:95]
	v_cndmask_b32_e64 v193, v193, v122, s[94:95]
	v_mov_b32_dpp v122, v120 quad_perm:[1,0,3,2] row_mask:0xf bank_mask:0xf
	v_mov_b32_dpp v123, v194 quad_perm:[1,0,3,2] row_mask:0xf bank_mask:0xf
	v_cndmask_b32_e64 v120, v123, v120, s[94:95]
	v_cndmask_b32_e64 v194, v194, v122, s[94:95]
	v_mov_b32_dpp v122, v121 quad_perm:[1,0,3,2] row_mask:0xf bank_mask:0xf
	v_mov_b32_dpp v123, v195 quad_perm:[1,0,3,2] row_mask:0xf bank_mask:0xf
	v_cndmask_b32_e64 v121, v123, v121, s[94:95]
	v_cndmask_b32_e64 v195, v195, v122, s[94:95]
; __device__ __forceinline__ unsigned cvt_pk_bf16(float lo, float hi) { unsigned r; asm volatile("v_cvt_pk_bf16_f32 %0, %1, %2" : "=v"(r) : "v"(lo), "v"(hi)); return r; }
;     __device__ __forceinline__ void operator()(const f32x4 (&acc)[2][2][4][2], const pg8::Unit& u, int wr, int wc, int fr, int fq) const {
;     ...
;             for (int k = 0; k < 12; ++k) {
;                 if (k < 4 || k >= 8) {
;                     const int ai = k >> 3, m = k & 3;
;                     const int row = row0 + ai * 128 + m * 16;
;                     const f32x4 c0 = c[0] * osc, c1 = c[1] * osc, s0 = sn[0] * osc, s1 = sn[1] * osc;
;                     const f32x4 a0 = acc[ai][0][m][0], a1 = acc[ai][0][m][1], b0 = acc[ai][1][m][0], b1 = acc[ai][1][m][1];
;                     const f32x4 o10 = a0 * c0 - b0 * s0, o11 = a1 * c1 - b1 * s1, o20 = a0 * s0 + b0 * c0, o21 = a1 * s1 + b1 * c1;
;                     bf16_t* rowp = base + (size_t)row * 512 + col0;
;                     u32x4 w; w.x = cvt_pk_bf16(o10[0], o10[1]); w.y = cvt_pk_bf16(o10[2], o10[3]); w.z = cvt_pk_bf16(o11[0], o11[1]); w.w = cvt_pk_bf16(o11[2], o11[3]);
;                     *(u32x4*)(rowp) = w;
;                     w.x = cvt_pk_bf16(o20[0], o20[1]); w.y = cvt_pk_bf16(o20[2], o20[3]); w.z = cvt_pk_bf16(o21[0], o21[1]); w.w = cvt_pk_bf16(o21[2], o21[3]);
;                     *(u32x4*)(rowp + 64) = w;
;                 }
;                 if (k < 11) {
; #pragma unroll
;                     for (int e = 0; e < 2; ++e) { const f32x4 cn = c[e] * c16[e] - sn[e] * s16[e]; sn[e] = sn[e] * c16[e] + c[e] * s16[e]; c[e] = cn; } }
;             }
	global_store_dwordx4 v[124:125], v[118:121], off
	global_store_dwordx4 v[124:125], v[192:195], off offset:1024
	v_pk_mul_f32 v[178:179], v[144:145], v[202:203]
	s_nop 0
	v_pk_mul_f32 v[194:195], v[144:145], v[204:205]
	v_pk_mul_f32 v[192:193], v[142:143], v[200:201]
	v_pk_fma_f32 v[178:179], v[140:141], v[204:205], v[178:179] neg_lo:[0,0,1] neg_hi:[0,0,1]
	v_pk_mul_f32 v[204:205], v[142:143], v[206:207]
	v_pk_fma_f32 v[194:195], v[140:141], v[202:203], v[194:195]
	v_pk_mul_f32 v[202:203], v[136:137], v[196:197]
	v_pk_fma_f32 v[192:193], v[138:139], v[206:207], v[192:193] neg_lo:[0,0,1] neg_hi:[0,0,1]
	v_pk_fma_f32 v[200:201], v[138:139], v[200:201], v[204:205]
	v_pk_fma_f32 v[202:203], v[132:133], v[208:209], v[202:203] neg_lo:[0,0,1] neg_hi:[0,0,1]
	v_pk_mul_f32 v[206:207], v[136:137], v[208:209]
	v_pk_mul_f32 v[208:209], v[134:135], v[210:211]
	v_pk_mul_f32 v[204:205], v[134:135], v[198:199]
	v_pk_fma_f32 v[196:197], v[132:133], v[196:197], v[206:207]
	v_pk_fma_f32 v[198:199], v[130:131], v[198:199], v[208:209]
	v_pk_mul_f32 v[206:207], v[144:145], v[194:195]
	v_pk_mul_f32 v[208:209], v[142:143], v[200:201]
	v_pk_fma_f32 v[206:207], v[140:141], v[178:179], v[206:207] neg_lo:[0,0,1] neg_hi:[0,0,1]
	v_pk_fma_f32 v[208:209], v[138:139], v[192:193], v[208:209] neg_lo:[0,0,1] neg_hi:[0,0,1]
	v_pk_mul_f32 v[178:179], v[144:145], v[178:179]
	v_pk_mul_f32 v[192:193], v[142:143], v[192:193]
	v_pk_fma_f32 v[204:205], v[130:131], v[210:211], v[204:205] neg_lo:[0,0,1] neg_hi:[0,0,1]
	v_pk_fma_f32 v[178:179], v[140:141], v[194:195], v[178:179]
	v_pk_fma_f32 v[192:193], v[138:139], v[200:201], v[192:193]
	v_pk_mul_f32 v[194:195], v[136:137], v[196:197]
	v_pk_mul_f32 v[200:201], v[134:135], v[198:199]
	v_pk_fma_f32 v[194:195], v[132:133], v[202:203], v[194:195] neg_lo:[0,0,1] neg_hi:[0,0,1]
	v_pk_fma_f32 v[200:201], v[130:131], v[204:205], v[200:201] neg_lo:[0,0,1] neg_hi:[0,0,1]
	v_pk_mul_f32 v[202:203], v[136:137], v[202:203]
	v_pk_mul_f32 v[204:205], v[134:135], v[204:205]
	v_pk_fma_f32 v[196:197], v[132:133], v[196:197], v[202:203]
	v_pk_fma_f32 v[198:199], v[130:131], v[198:199], v[204:205]
	v_pk_mul_f32 v[202:203], v[144:145], v[178:179]
	v_pk_mul_f32 v[204:205], v[142:143], v[192:193]
	v_pk_fma_f32 v[202:203], v[140:141], v[206:207], v[202:203] neg_lo:[0,0,1] neg_hi:[0,0,1]
	v_pk_fma_f32 v[204:205], v[138:139], v[208:209], v[204:205] neg_lo:[0,0,1] neg_hi:[0,0,1]
	v_pk_mul_f32 v[206:207], v[144:145], v[206:207]
	v_pk_mul_f32 v[208:209], v[142:143], v[208:209]
	v_pk_fma_f32 v[178:179], v[140:141], v[178:179], v[206:207]
	v_pk_fma_f32 v[192:193], v[138:139], v[192:193], v[208:209]
	v_pk_mul_f32 v[206:207], v[136:137], v[196:197]
	v_pk_mul_f32 v[208:209], v[134:135], v[198:199]
	v_pk_fma_f32 v[206:207], v[132:133], v[194:195], v[206:207] neg_lo:[0,0,1] neg_hi:[0,0,1]
	v_pk_fma_f32 v[208:209], v[130:131], v[200:201], v[208:209] neg_lo:[0,0,1] neg_hi:[0,0,1]
	v_pk_mul_f32 v[194:195], v[136:137], v[194:195]
	v_pk_mul_f32 v[200:201], v[134:135], v[200:201]
	v_pk_fma_f32 v[194:195], v[132:133], v[196:197], v[194:195]
	v_pk_fma_f32 v[196:197], v[130:131], v[198:199], v[200:201]
	v_pk_mul_f32 v[198:199], v[144:145], v[178:179]
	v_pk_mul_f32 v[200:201], v[142:143], v[192:193]
	v_pk_fma_f32 v[198:199], v[140:141], v[202:203], v[198:199] neg_lo:[0,0,1] neg_hi:[0,0,1]
	v_pk_fma_f32 v[200:201], v[138:139], v[204:205], v[200:201] neg_lo:[0,0,1] neg_hi:[0,0,1]
	v_pk_mul_f32 v[202:203], v[144:145], v[202:203]
	v_pk_mul_f32 v[204:205], v[142:143], v[204:205]
	v_pk_fma_f32 v[178:179], v[140:141], v[178:179], v[202:203]
	v_pk_fma_f32 v[192:193], v[138:139], v[192:193], v[204:205]
	v_pk_mul_f32 v[202:203], v[136:137], v[194:195]
	v_pk_mul_f32 v[204:205], v[134:135], v[196:197]
	v_pk_fma_f32 v[202:203], v[132:133], v[206:207], v[202:203] neg_lo:[0,0,1] neg_hi:[0,0,1]
	v_pk_fma_f32 v[204:205], v[130:131], v[208:209], v[204:205] neg_lo:[0,0,1] neg_hi:[0,0,1]
	v_pk_mul_f32 v[206:207], v[136:137], v[206:207]
	v_pk_mul_f32 v[208:209], v[134:135], v[208:209]
	v_pk_fma_f32 v[194:195], v[132:133], v[194:195], v[206:207]
	v_pk_fma_f32 v[196:197], v[130:131], v[196:197], v[208:209]
	v_pk_mul_f32 v[206:207], v[144:145], v[178:179]
	v_pk_mul_f32 v[208:209], v[142:143], v[192:193]
	v_pk_fma_f32 v[206:207], v[140:141], v[198:199], v[206:207] neg_lo:[0,0,1] neg_hi:[0,0,1]
	v_pk_fma_f32 v[208:209], v[138:139], v[200:201], v[208:209] neg_lo:[0,0,1] neg_hi:[0,0,1]
	v_pk_mul_f32 v[198:199], v[144:145], v[198:199]
	v_pk_mul_f32 v[200:201], v[142:143], v[200:201]
	v_pk_fma_f32 v[178:179], v[140:141], v[178:179], v[198:199]
	v_pk_fma_f32 v[198:199], v[138:139], v[192:193], v[200:201]
	v_pk_mul_f32 v[192:193], v[136:137], v[194:195]
	v_pk_mul_f32 v[200:201], v[134:135], v[196:197]
	v_pk_fma_f32 v[210:211], v[132:133], v[202:203], v[192:193] neg_lo:[0,0,1] neg_hi:[0,0,1]
	v_pk_mul_f32 v[192:193], v[136:137], v[202:203]
	v_pk_mul_f32 v[202:203], v[134:135], v[204:205]
	v_pk_mul_f32 v[216:217], v[176:177], v[198:199] op_sel_hi:[0,1]
	v_pk_fma_f32 v[200:201], v[130:131], v[204:205], v[200:201] neg_lo:[0,0,1] neg_hi:[0,0,1]
	v_pk_fma_f32 v[204:205], v[132:133], v[194:195], v[192:193]
	v_pk_fma_f32 v[196:197], v[130:131], v[196:197], v[202:203]
	v_pk_mul_f32 v[194:195], v[176:177], v[208:209] op_sel_hi:[0,1]
	v_pk_mul_f32 v[214:215], v[176:177], v[178:179] op_sel_hi:[0,1]
	v_pk_mul_f32 v[224:225], v[54:55], v[216:217]
	v_pk_mul_f32 v[192:193], v[176:177], v[206:207] op_sel_hi:[0,1]
	v_pk_mul_f32 v[212:213], v[176:177], v[200:201] op_sel_hi:[0,1]
	v_pk_mul_f32 v[220:221], v[176:177], v[196:197] op_sel_hi:[0,1]
	v_pk_mul_f32 v[222:223], v[56:57], v[214:215]
; __device__ __forceinline__ unsigned cvt_pk_bf16(float lo, float hi) { unsigned r; asm volatile("v_cvt_pk_bf16_f32 %0, %1, %2" : "=v"(r) : "v"(lo), "v"(hi)); return r; }
;     __device__ __forceinline__ void operator()(const f32x4 (&acc)[2][2][4][2], const pg8::Unit& u, int wr, int wc, int fr, int fq) const {
;     ...
;             for (int k = 0; k < 12; ++k) {
;                 if (k < 4 || k >= 8) {
;                     const int ai = k >> 3, m = k & 3;
;                     const int row = row0 + ai * 128 + m * 16;
;                     const f32x4 c0 = c[0] * osc, c1 = c[1] * osc, s0 = sn[0] * osc, s1 = sn[1] * osc;
;                     const f32x4 a0 = acc[ai][0][m][0], a1 = acc[ai][0][m][1], b0 = acc[ai][1][m][0], b1 = acc[ai][1][m][1];
;                     const f32x4 o10 = a0 * c0 - b0 * s0, o11 = a1 * c1 - b1 * s1, o20 = a0 * s0 + b0 * c0, o21 = a1 * s1 + b1 * c1;
;                     bf16_t* rowp = base + (size_t)row * 512 + col0;
;                     u32x4 w; w.x = cvt_pk_bf16(o10[0], o10[1]); w.y = cvt_pk_bf16(o10[2], o10[3]); w.z = cvt_pk_bf16(o11[0], o11[1]); w.w = cvt_pk_bf16(o11[2], o11[3]);
;                     *(u32x4*)(rowp) = w;
;                     w.x = cvt_pk_bf16(o20[0], o20[1]); w.y = cvt_pk_bf16(o20[2], o20[3]); w.z = cvt_pk_bf16(o21[0], o21[1]); w.w = cvt_pk_bf16(o21[2], o21[3]);
;                     *(u32x4*)(rowp + 64) = w;
;                 }
;                 if (k < 11) {
; #pragma unroll
;                     for (int e = 0; e < 2; ++e) { const f32x4 cn = c[e] * c16[e] - sn[e] * s16[e]; sn[e] = sn[e] * c16[e] + c[e] * s16[e]; c[e] = cn; } }
;             }
	v_pk_fma_f32 v[224:225], v[62:63], v[194:195], v[224:225] neg_lo:[0,0,1] neg_hi:[0,0,1]
	v_pk_mul_f32 v[194:195], v[54:55], v[194:195]
	v_pk_mul_f32 v[202:203], v[176:177], v[210:211] op_sel_hi:[0,1]
	v_pk_mul_f32 v[218:219], v[176:177], v[204:205] op_sel_hi:[0,1]
	v_pk_fma_f32 v[222:223], v[64:65], v[192:193], v[222:223] neg_lo:[0,0,1] neg_hi:[0,0,1]
	v_pk_mul_f32 v[228:229], v[50:51], v[220:221]
	v_pk_mul_f32 v[192:193], v[56:57], v[192:193]
	v_pk_fma_f32 v[216:217], v[62:63], v[216:217], v[194:195]
	v_pk_mul_f32 v[194:195], v[50:51], v[212:213]
	v_pk_mul_f32 v[226:227], v[52:53], v[218:219]
	v_pk_fma_f32 v[228:229], v[58:59], v[212:213], v[228:229] neg_lo:[0,0,1] neg_hi:[0,0,1]
	v_pk_fma_f32 v[214:215], v[64:65], v[214:215], v[192:193]
	v_pk_mul_f32 v[192:193], v[52:53], v[202:203]
	v_pk_fma_f32 v[212:213], v[58:59], v[220:221], v[194:195]
	v_add_co_u32_e32 v220, vcc, s87, v174
	v_pk_fma_f32 v[226:227], v[60:61], v[202:203], v[226:227] neg_lo:[0,0,1] neg_hi:[0,0,1]
	v_pk_fma_f32 v[202:203], v[60:61], v[218:219], v[192:193]
	v_cvt_pk_bf16_f32 v192, v224, v225
	v_cvt_pk_bf16_f32 v193, v222, v223
	v_cvt_pk_bf16_f32 v194, v228, v229
	v_cvt_pk_bf16_f32 v195, v226, v227
	v_addc_co_u32_e32 v221, vcc, 0, v175, vcc
	v_lshl_add_u64 v[218:219], v[174:175], 0, s[16:17]
	v_mov_b32_e32 v118, v192
	v_mov_b32_e32 v119, v193
	v_mov_b32_e32 v120, v194
	v_mov_b32_e32 v121, v195
	v_lshl_add_u64 v[124:125], v[220:221], 0, v[252:253]
	s_nop 1
	v_cvt_pk_bf16_f32 v192, v216, v217
	v_cvt_pk_bf16_f32 v193, v214, v215
	v_cvt_pk_bf16_f32 v194, v212, v213
	v_cvt_pk_bf16_f32 v195, v202, v203
	s_nop 1
	v_mov_b32_dpp v122, v118 quad_perm:[1,0,3,2] row_mask:0xf bank_mask:0xf
	v_mov_b32_dpp v123, v192 quad_perm:[1,0,3,2] row_mask:0xf bank_mask:0xf
	v_cndmask_b32_e64 v118, v123, v118, s[94:95]
	v_cndmask_b32_e64 v192, v192, v122, s[94:95]
	v_mov_b32_dpp v122, v119 quad_perm:[1,0,3,2] row_mask:0xf bank_mask:0xf
	v_mov_b32_dpp v123, v193 quad_perm:[1,0,3,2] row_mask:0xf bank_mask:0xf
	v_cndmask_b32_e64 v119, v123, v119, s[94:95]
	v_cndmask_b32_e64 v193, v193, v122, s[94:95]
	v_mov_b32_dpp v122, v120 quad_perm:[1,0,3,2] row_mask:0xf bank_mask:0xf
	v_mov_b32_dpp v123, v194 quad_perm:[1,0,3,2] row_mask:0xf bank_mask:0xf
	v_cndmask_b32_e64 v120, v123, v120, s[94:95]
	v_cndmask_b32_e64 v194, v194, v122, s[94:95]
	v_mov_b32_dpp v122, v121 quad_perm:[1,0,3,2] row_mask:0xf bank_mask:0xf
	v_mov_b32_dpp v123, v195 quad_perm:[1,0,3,2] row_mask:0xf bank_mask:0xf
	v_cndmask_b32_e64 v121, v123, v121, s[94:95]
	v_cndmask_b32_e64 v195, v195, v122, s[94:95]
	global_store_dwordx4 v[124:125], v[118:121], off
	global_store_dwordx4 v[124:125], v[192:195], off offset:1024
	s_nop 1
	v_pk_mul_f32 v[194:195], v[142:143], v[198:199]
	v_pk_mul_f32 v[192:193], v[144:145], v[178:179]
	v_pk_fma_f32 v[212:213], v[138:139], v[208:209], v[194:195] neg_lo:[0,0,1] neg_hi:[0,0,1]
	v_pk_mul_f32 v[194:195], v[142:143], v[208:209]
	v_pk_fma_f32 v[202:203], v[140:141], v[206:207], v[192:193] neg_lo:[0,0,1] neg_hi:[0,0,1]
	v_pk_mul_f32 v[192:193], v[144:145], v[206:207]
	v_pk_fma_f32 v[198:199], v[138:139], v[198:199], v[194:195]
	v_pk_mul_f32 v[194:195], v[134:135], v[196:197]
	v_pk_fma_f32 v[178:179], v[140:141], v[178:179], v[192:193]
	v_pk_mul_f32 v[192:193], v[136:137], v[204:205]
	v_pk_fma_f32 v[208:209], v[130:131], v[200:201], v[194:195] neg_lo:[0,0,1] neg_hi:[0,0,1]
	v_pk_mul_f32 v[194:195], v[134:135], v[200:201]
	v_pk_mul_f32 v[216:217], v[176:177], v[198:199] op_sel_hi:[0,1]
	v_pk_fma_f32 v[206:207], v[132:133], v[210:211], v[192:193] neg_lo:[0,0,1] neg_hi:[0,0,1]
	v_pk_mul_f32 v[192:193], v[136:137], v[210:211]
	v_pk_fma_f32 v[196:197], v[130:131], v[196:197], v[194:195]
	v_pk_mul_f32 v[194:195], v[176:177], v[212:213] op_sel_hi:[0,1]
	v_pk_mul_f32 v[214:215], v[176:177], v[178:179] op_sel_hi:[0,1]
	v_pk_mul_f32 v[224:225], v[38:39], v[216:217]
	v_pk_fma_f32 v[200:201], v[132:133], v[204:205], v[192:193]
	v_pk_mul_f32 v[192:193], v[176:177], v[202:203] op_sel_hi:[0,1]
	v_pk_mul_f32 v[210:211], v[176:177], v[208:209] op_sel_hi:[0,1]
	v_pk_mul_f32 v[220:221], v[176:177], v[196:197] op_sel_hi:[0,1]
	v_pk_mul_f32 v[222:223], v[40:41], v[214:215]
	v_pk_fma_f32 v[224:225], v[46:47], v[194:195], v[224:225] neg_lo:[0,0,1] neg_hi:[0,0,1]
	v_pk_mul_f32 v[194:195], v[38:39], v[194:195]
	v_pk_mul_f32 v[204:205], v[176:177], v[206:207] op_sel_hi:[0,1]
	v_pk_mul_f32 v[218:219], v[176:177], v[200:201] op_sel_hi:[0,1]
	v_pk_fma_f32 v[222:223], v[48:49], v[192:193], v[222:223] neg_lo:[0,0,1] neg_hi:[0,0,1]
	v_pk_mul_f32 v[228:229], v[34:35], v[220:221]
	v_pk_mul_f32 v[192:193], v[40:41], v[192:193]
	v_pk_fma_f32 v[216:217], v[46:47], v[216:217], v[194:195]
	v_pk_mul_f32 v[194:195], v[34:35], v[210:211]
	v_pk_mul_f32 v[226:227], v[36:37], v[218:219]
	v_pk_fma_f32 v[228:229], v[42:43], v[210:211], v[228:229] neg_lo:[0,0,1] neg_hi:[0,0,1]
	v_pk_fma_f32 v[214:215], v[48:49], v[214:215], v[192:193]
	v_pk_mul_f32 v[192:193], v[36:37], v[204:205]
	v_pk_fma_f32 v[210:211], v[42:43], v[220:221], v[194:195]
	v_add_co_u32_e32 v220, vcc, s88, v174
	v_pk_fma_f32 v[226:227], v[44:45], v[204:205], v[226:227] neg_lo:[0,0,1] neg_hi:[0,0,1]
	v_pk_fma_f32 v[204:205], v[44:45], v[218:219], v[192:193]
	v_cvt_pk_bf16_f32 v192, v224, v225
	v_cvt_pk_bf16_f32 v193, v222, v223
	v_cvt_pk_bf16_f32 v194, v228, v229
	v_cvt_pk_bf16_f32 v195, v226, v227
	v_addc_co_u32_e32 v221, vcc, 0, v175, vcc
	v_lshl_add_u64 v[218:219], v[174:175], 0, s[18:19]
	v_mov_b32_e32 v118, v192
	v_mov_b32_e32 v119, v193
	v_mov_b32_e32 v120, v194
	v_mov_b32_e32 v121, v195
	v_lshl_add_u64 v[124:125], v[220:221], 0, v[252:253]
	s_nop 1
	v_cvt_pk_bf16_f32 v192, v216, v217
; __device__ __forceinline__ unsigned cvt_pk_bf16(float lo, float hi) { unsigned r; asm volatile("v_cvt_pk_bf16_f32 %0, %1, %2" : "=v"(r) : "v"(lo), "v"(hi)); return r; }
;     __device__ __forceinline__ void operator()(const f32x4 (&acc)[2][2][4][2], const pg8::Unit& u, int wr, int wc, int fr, int fq) const {
;     ...
;             for (int k = 0; k < 12; ++k) {
;                 if (k < 4 || k >= 8) {
;                     const int ai = k >> 3, m = k & 3;
;                     const int row = row0 + ai * 128 + m * 16;
;                     const f32x4 c0 = c[0] * osc, c1 = c[1] * osc, s0 = sn[0] * osc, s1 = sn[1] * osc;
;                     const f32x4 a0 = acc[ai][0][m][0], a1 = acc[ai][0][m][1], b0 = acc[ai][1][m][0], b1 = acc[ai][1][m][1];
;                     const f32x4 o10 = a0 * c0 - b0 * s0, o11 = a1 * c1 - b1 * s1, o20 = a0 * s0 + b0 * c0, o21 = a1 * s1 + b1 * c1;
;                     bf16_t* rowp = base + (size_t)row * 512 + col0;
;                     u32x4 w; w.x = cvt_pk_bf16(o10[0], o10[1]); w.y = cvt_pk_bf16(o10[2], o10[3]); w.z = cvt_pk_bf16(o11[0], o11[1]); w.w = cvt_pk_bf16(o11[2], o11[3]);
;                     *(u32x4*)(rowp) = w;
;                     w.x = cvt_pk_bf16(o20[0], o20[1]); w.y = cvt_pk_bf16(o20[2], o20[3]); w.z = cvt_pk_bf16(o21[0], o21[1]); w.w = cvt_pk_bf16(o21[2], o21[3]);
;                     *(u32x4*)(rowp + 64) = w;
;                 }
;                 if (k < 11) {
; #pragma unroll
;                     for (int e = 0; e < 2; ++e) { const f32x4 cn = c[e] * c16[e] - sn[e] * s16[e]; sn[e] = sn[e] * c16[e] + c[e] * s16[e]; c[e] = cn; } }
;             }
	v_cvt_pk_bf16_f32 v193, v214, v215
	v_cvt_pk_bf16_f32 v194, v210, v211
	v_cvt_pk_bf16_f32 v195, v204, v205
	s_nop 1
	v_mov_b32_dpp v122, v118 quad_perm:[1,0,3,2] row_mask:0xf bank_mask:0xf
	v_mov_b32_dpp v123, v192 quad_perm:[1,0,3,2] row_mask:0xf bank_mask:0xf
	v_cndmask_b32_e64 v118, v123, v118, s[94:95]
	v_cndmask_b32_e64 v192, v192, v122, s[94:95]
	v_mov_b32_dpp v122, v119 quad_perm:[1,0,3,2] row_mask:0xf bank_mask:0xf
	v_mov_b32_dpp v123, v193 quad_perm:[1,0,3,2] row_mask:0xf bank_mask:0xf
	v_cndmask_b32_e64 v119, v123, v119, s[94:95]
	v_cndmask_b32_e64 v193, v193, v122, s[94:95]
	v_mov_b32_dpp v122, v120 quad_perm:[1,0,3,2] row_mask:0xf bank_mask:0xf
	v_mov_b32_dpp v123, v194 quad_perm:[1,0,3,2] row_mask:0xf bank_mask:0xf
	v_cndmask_b32_e64 v120, v123, v120, s[94:95]
	v_cndmask_b32_e64 v194, v194, v122, s[94:95]
	v_mov_b32_dpp v122, v121 quad_perm:[1,0,3,2] row_mask:0xf bank_mask:0xf
	v_mov_b32_dpp v123, v195 quad_perm:[1,0,3,2] row_mask:0xf bank_mask:0xf
	v_cndmask_b32_e64 v121, v123, v121, s[94:95]
	v_cndmask_b32_e64 v195, v195, v122, s[94:95]
	global_store_dwordx4 v[124:125], v[118:121], off
	global_store_dwordx4 v[124:125], v[192:195], off offset:1024
	s_nop 1
	v_pk_mul_f32 v[194:195], v[142:143], v[198:199]
	v_pk_mul_f32 v[192:193], v[144:145], v[178:179]
	v_pk_fma_f32 v[210:211], v[138:139], v[212:213], v[194:195] neg_lo:[0,0,1] neg_hi:[0,0,1]
	v_pk_mul_f32 v[194:195], v[142:143], v[212:213]
	v_pk_fma_f32 v[204:205], v[140:141], v[202:203], v[192:193] neg_lo:[0,0,1] neg_hi:[0,0,1]
	v_pk_mul_f32 v[192:193], v[144:145], v[202:203]
	v_pk_fma_f32 v[198:199], v[138:139], v[198:199], v[194:195]
	v_pk_mul_f32 v[194:195], v[134:135], v[196:197]
	v_pk_fma_f32 v[178:179], v[140:141], v[178:179], v[192:193]
	v_pk_mul_f32 v[192:193], v[136:137], v[200:201]
	v_pk_fma_f32 v[212:213], v[130:131], v[208:209], v[194:195] neg_lo:[0,0,1] neg_hi:[0,0,1]
	v_pk_mul_f32 v[194:195], v[134:135], v[208:209]
	v_pk_mul_f32 v[216:217], v[176:177], v[198:199] op_sel_hi:[0,1]
	v_pk_fma_f32 v[202:203], v[132:133], v[206:207], v[192:193] neg_lo:[0,0,1] neg_hi:[0,0,1]
	v_pk_mul_f32 v[192:193], v[136:137], v[206:207]
	v_pk_fma_f32 v[196:197], v[130:131], v[196:197], v[194:195]
	v_pk_mul_f32 v[194:195], v[176:177], v[210:211] op_sel_hi:[0,1]
	v_pk_mul_f32 v[214:215], v[176:177], v[178:179] op_sel_hi:[0,1]
	v_pk_mul_f32 v[224:225], v[22:23], v[216:217]
	v_pk_fma_f32 v[200:201], v[132:133], v[200:201], v[192:193]
	v_pk_mul_f32 v[192:193], v[176:177], v[204:205] op_sel_hi:[0,1]
	v_pk_mul_f32 v[208:209], v[176:177], v[212:213] op_sel_hi:[0,1]
	v_pk_mul_f32 v[220:221], v[176:177], v[196:197] op_sel_hi:[0,1]
	v_pk_mul_f32 v[222:223], v[24:25], v[214:215]
	v_pk_fma_f32 v[224:225], v[30:31], v[194:195], v[224:225] neg_lo:[0,0,1] neg_hi:[0,0,1]
	v_pk_mul_f32 v[194:195], v[22:23], v[194:195]
	v_pk_mul_f32 v[206:207], v[176:177], v[202:203] op_sel_hi:[0,1]
	v_pk_mul_f32 v[218:219], v[176:177], v[200:201] op_sel_hi:[0,1]
	v_pk_fma_f32 v[222:223], v[32:33], v[192:193], v[222:223] neg_lo:[0,0,1] neg_hi:[0,0,1]
	v_pk_mul_f32 v[228:229], v[18:19], v[220:221]
	v_pk_mul_f32 v[192:193], v[24:25], v[192:193]
	v_pk_fma_f32 v[216:217], v[30:31], v[216:217], v[194:195]
	v_pk_mul_f32 v[194:195], v[18:19], v[208:209]
	v_pk_mul_f32 v[226:227], v[20:21], v[218:219]
	v_pk_fma_f32 v[228:229], v[26:27], v[208:209], v[228:229] neg_lo:[0,0,1] neg_hi:[0,0,1]
	v_pk_fma_f32 v[214:215], v[32:33], v[214:215], v[192:193]
	v_pk_mul_f32 v[192:193], v[20:21], v[206:207]
	v_pk_fma_f32 v[208:209], v[26:27], v[220:221], v[194:195]
	v_add_co_u32_e32 v220, vcc, s89, v174
	v_pk_fma_f32 v[226:227], v[28:29], v[206:207], v[226:227] neg_lo:[0,0,1] neg_hi:[0,0,1]
	v_pk_fma_f32 v[206:207], v[28:29], v[218:219], v[192:193]
	v_cvt_pk_bf16_f32 v192, v224, v225
	v_cvt_pk_bf16_f32 v193, v222, v223
	v_cvt_pk_bf16_f32 v194, v228, v229
	v_cvt_pk_bf16_f32 v195, v226, v227
	v_addc_co_u32_e32 v221, vcc, 0, v175, vcc
	v_lshl_add_u64 v[218:219], v[174:175], 0, s[20:21]
	v_mov_b32_e32 v118, v192
	v_mov_b32_e32 v119, v193
	v_mov_b32_e32 v120, v194
	v_mov_b32_e32 v121, v195
	v_lshl_add_u64 v[124:125], v[220:221], 0, v[252:253]
	s_nop 1
	v_cvt_pk_bf16_f32 v192, v216, v217
	v_cvt_pk_bf16_f32 v193, v214, v215
	v_cvt_pk_bf16_f32 v194, v208, v209
	v_cvt_pk_bf16_f32 v195, v206, v207
	s_nop 1
	v_mov_b32_dpp v122, v118 quad_perm:[1,0,3,2] row_mask:0xf bank_mask:0xf
	v_mov_b32_dpp v123, v192 quad_perm:[1,0,3,2] row_mask:0xf bank_mask:0xf
	v_cndmask_b32_e64 v118, v123, v118, s[94:95]
	v_cndmask_b32_e64 v192, v192, v122, s[94:95]
	v_mov_b32_dpp v122, v119 quad_perm:[1,0,3,2] row_mask:0xf bank_mask:0xf
	v_mov_b32_dpp v123, v193 quad_perm:[1,0,3,2] row_mask:0xf bank_mask:0xf
	v_cndmask_b32_e64 v119, v123, v119, s[94:95]
	v_cndmask_b32_e64 v193, v193, v122, s[94:95]
; __device__ __forceinline__ unsigned cvt_pk_bf16(float lo, float hi) { unsigned r; asm volatile("v_cvt_pk_bf16_f32 %0, %1, %2" : "=v"(r) : "v"(lo), "v"(hi)); return r; }
;     __device__ __forceinline__ void operator()(const f32x4 (&acc)[2][2][4][2], const pg8::Unit& u, int wr, int wc, int fr, int fq) const {
;     ...
;             for (int k = 0; k < 12; ++k) {
;                 if (k < 4 || k >= 8) {
;                     const int ai = k >> 3, m = k & 3;
;                     const int row = row0 + ai * 128 + m * 16;
;                     const f32x4 c0 = c[0] * osc, c1 = c[1] * osc, s0 = sn[0] * osc, s1 = sn[1] * osc;
;                     const f32x4 a0 = acc[ai][0][m][0], a1 = acc[ai][0][m][1], b0 = acc[ai][1][m][0], b1 = acc[ai][1][m][1];
;                     const f32x4 o10 = a0 * c0 - b0 * s0, o11 = a1 * c1 - b1 * s1, o20 = a0 * s0 + b0 * c0, o21 = a1 * s1 + b1 * c1;
;                     bf16_t* rowp = base + (size_t)row * 512 + col0;
;                     u32x4 w; w.x = cvt_pk_bf16(o10[0], o10[1]); w.y = cvt_pk_bf16(o10[2], o10[3]); w.z = cvt_pk_bf16(o11[0], o11[1]); w.w = cvt_pk_bf16(o11[2], o11[3]);
;                     *(u32x4*)(rowp) = w;
;                     w.x = cvt_pk_bf16(o20[0], o20[1]); w.y = cvt_pk_bf16(o20[2], o20[3]); w.z = cvt_pk_bf16(o21[0], o21[1]); w.w = cvt_pk_bf16(o21[2], o21[3]);
;                     *(u32x4*)(rowp + 64) = w;
;                 }
;                 if (k < 11) {
; #pragma unroll
;                     for (int e = 0; e < 2; ++e) { const f32x4 cn = c[e] * c16[e] - sn[e] * s16[e]; sn[e] = sn[e] * c16[e] + c[e] * s16[e]; c[e] = cn; } }
;             }
	v_mov_b32_dpp v122, v120 quad_perm:[1,0,3,2] row_mask:0xf bank_mask:0xf
	v_mov_b32_dpp v123, v194 quad_perm:[1,0,3,2] row_mask:0xf bank_mask:0xf
	v_cndmask_b32_e64 v120, v123, v120, s[94:95]
	v_cndmask_b32_e64 v194, v194, v122, s[94:95]
	v_mov_b32_dpp v122, v121 quad_perm:[1,0,3,2] row_mask:0xf bank_mask:0xf
	v_mov_b32_dpp v123, v195 quad_perm:[1,0,3,2] row_mask:0xf bank_mask:0xf
	v_cndmask_b32_e64 v121, v123, v121, s[94:95]
	v_cndmask_b32_e64 v195, v195, v122, s[94:95]
	global_store_dwordx4 v[124:125], v[118:121], off
	global_store_dwordx4 v[124:125], v[192:195], off offset:1024
	s_nop 1
	v_pk_mul_f32 v[192:193], v[144:145], v[178:179]
	v_pk_mul_f32 v[194:195], v[142:143], v[198:199]
	v_pk_mul_f32 v[144:145], v[144:145], v[204:205]
	v_pk_mul_f32 v[142:143], v[142:143], v[210:211]
	v_pk_fma_f32 v[192:193], v[140:141], v[204:205], v[192:193] neg_lo:[0,0,1] neg_hi:[0,0,1]
	v_pk_fma_f32 v[194:195], v[138:139], v[210:211], v[194:195] neg_lo:[0,0,1] neg_hi:[0,0,1]
	v_pk_fma_f32 v[140:141], v[140:141], v[178:179], v[144:145]
	v_pk_fma_f32 v[138:139], v[138:139], v[198:199], v[142:143]
	v_pk_mul_f32 v[142:143], v[136:137], v[200:201]
	v_pk_mul_f32 v[144:145], v[134:135], v[196:197]
	v_pk_mul_f32 v[136:137], v[136:137], v[202:203]
	v_pk_mul_f32 v[134:135], v[134:135], v[212:213]
	v_pk_fma_f32 v[142:143], v[132:133], v[202:203], v[142:143] neg_lo:[0,0,1] neg_hi:[0,0,1]
	v_pk_fma_f32 v[144:145], v[130:131], v[212:213], v[144:145] neg_lo:[0,0,1] neg_hi:[0,0,1]
	v_pk_fma_f32 v[132:133], v[132:133], v[200:201], v[136:137]
	v_pk_fma_f32 v[130:131], v[130:131], v[196:197], v[134:135]
	v_pk_mul_f32 v[140:141], v[176:177], v[140:141] op_sel_hi:[0,1]
	v_pk_mul_f32 v[138:139], v[176:177], v[138:139] op_sel_hi:[0,1]
	v_pk_mul_f32 v[134:135], v[176:177], v[192:193] op_sel_hi:[0,1]
	v_pk_mul_f32 v[136:137], v[176:177], v[194:195] op_sel_hi:[0,1]
	v_pk_mul_f32 v[142:143], v[176:177], v[142:143] op_sel_hi:[0,1]
	v_pk_mul_f32 v[144:145], v[176:177], v[144:145] op_sel_hi:[0,1]
	v_pk_mul_f32 v[132:133], v[176:177], v[132:133] op_sel_hi:[0,1]
	v_pk_mul_f32 v[130:131], v[176:177], v[130:131] op_sel_hi:[0,1]
	v_pk_mul_f32 v[176:177], v[8:9], v[140:141]
	v_pk_mul_f32 v[178:179], v[6:7], v[138:139]
	v_pk_fma_f32 v[176:177], v[16:17], v[134:135], v[176:177] neg_lo:[0,0,1] neg_hi:[0,0,1]
	v_pk_fma_f32 v[178:179], v[14:15], v[136:137], v[178:179] neg_lo:[0,0,1] neg_hi:[0,0,1]
	v_pk_mul_f32 v[194:195], v[2:3], v[130:131]
	v_pk_mul_f32 v[134:135], v[8:9], v[134:135]
	v_pk_mul_f32 v[136:137], v[6:7], v[136:137]
	v_pk_mul_f32 v[192:193], v[4:5], v[132:133]
	v_pk_fma_f32 v[194:195], v[10:11], v[144:145], v[194:195] neg_lo:[0,0,1] neg_hi:[0,0,1]
	v_pk_fma_f32 v[134:135], v[16:17], v[140:141], v[134:135]
	v_pk_fma_f32 v[136:137], v[14:15], v[138:139], v[136:137]
	v_pk_mul_f32 v[138:139], v[4:5], v[142:143]
	v_pk_mul_f32 v[140:141], v[2:3], v[144:145]
	v_add_co_u32_e32 v144, vcc, s90, v174
	v_pk_fma_f32 v[192:193], v[12:13], v[142:143], v[192:193] neg_lo:[0,0,1] neg_hi:[0,0,1]
	v_pk_fma_f32 v[138:139], v[12:13], v[132:133], v[138:139]
	v_pk_fma_f32 v[140:141], v[10:11], v[130:131], v[140:141]
	v_lshl_add_u64 v[142:143], v[174:175], 0, s[24:25]
	v_cvt_pk_bf16_f32 v130, v178, v179
	v_cvt_pk_bf16_f32 v131, v176, v177
	v_cvt_pk_bf16_f32 v132, v194, v195
	v_cvt_pk_bf16_f32 v133, v192, v193
	v_addc_co_u32_e32 v145, vcc, 0, v175, vcc
	v_mov_b32_e32 v118, v130
	v_mov_b32_e32 v119, v131
	v_mov_b32_e32 v120, v132
	v_mov_b32_e32 v121, v133
	v_lshl_add_u64 v[124:125], v[144:145], 0, v[252:253]
	s_nop 1
	v_cvt_pk_bf16_f32 v130, v136, v137
	v_cvt_pk_bf16_f32 v131, v134, v135
	v_cvt_pk_bf16_f32 v132, v140, v141
	v_cvt_pk_bf16_f32 v133, v138, v139
	s_nop 1
	v_mov_b32_dpp v122, v118 quad_perm:[1,0,3,2] row_mask:0xf bank_mask:0xf
	v_mov_b32_dpp v123, v130 quad_perm:[1,0,3,2] row_mask:0xf bank_mask:0xf
	v_cndmask_b32_e64 v118, v123, v118, s[94:95]
	v_cndmask_b32_e64 v130, v130, v122, s[94:95]
	v_mov_b32_dpp v122, v119 quad_perm:[1,0,3,2] row_mask:0xf bank_mask:0xf
	v_mov_b32_dpp v123, v131 quad_perm:[1,0,3,2] row_mask:0xf bank_mask:0xf
	v_cndmask_b32_e64 v119, v123, v119, s[94:95]
	v_cndmask_b32_e64 v131, v131, v122, s[94:95]
	v_mov_b32_dpp v122, v120 quad_perm:[1,0,3,2] row_mask:0xf bank_mask:0xf
	v_mov_b32_dpp v123, v132 quad_perm:[1,0,3,2] row_mask:0xf bank_mask:0xf
	v_cndmask_b32_e64 v120, v123, v120, s[94:95]
	v_cndmask_b32_e64 v132, v132, v122, s[94:95]
	v_mov_b32_dpp v122, v121 quad_perm:[1,0,3,2] row_mask:0xf bank_mask:0xf
	v_mov_b32_dpp v123, v133 quad_perm:[1,0,3,2] row_mask:0xf bank_mask:0xf
	v_cndmask_b32_e64 v121, v123, v121, s[94:95]
	v_cndmask_b32_e64 v133, v133, v122, s[94:95]
	global_store_dwordx4 v[124:125], v[118:121], off
	global_store_dwordx4 v[124:125], v[130:133], off offset:1024
